# phase-0 outputs stored write-through (sc1) so the first grid barrier has little to write back
# baseline (speedup 1.0000x reference)
.Lp0_offok:
	s_bitcmp1_b32 s9, 0
	s_cbranch_scc1 .Lp0_gate
	s_mov_b32 s16, s12
	s_mov_b32 s17, s13
	s_add_u32 s18, s16, s14
	s_addc_u32 s19, s17, 0
	s_add_u32 s20, s18, s14
	s_addc_u32 s21, s19, 0
	s_add_u32 s22, s20, s14
	s_addc_u32 s23, s21, 0
	s_add_u32 s24, s22, s14
	s_addc_u32 s25, s23, 0
	s_add_u32 s26, s24, s14
	s_addc_u32 s27, s25, 0
	s_add_u32 s28, s26, s14
	s_addc_u32 s29, s27, 0
	s_add_u32 s30, s28, s14
	s_addc_u32 s31, s29, 0
	global_load_dwordx4 v[16:19], v4, s[16:17]
	global_load_dwordx4 v[20:23], v4, s[18:19]
	global_load_dwordx4 v[24:27], v4, s[20:21]
	global_load_dwordx4 v[28:31], v4, s[22:23]
	global_load_dwordx4 v[32:35], v4, s[24:25]
	global_load_dwordx4 v[36:39], v4, s[26:27]
	global_load_dwordx4 v[40:43], v4, s[28:29]
	global_load_dwordx4 v[44:47], v4, s[30:31]
	s_sub_u32 s0, s8, 1
	s_min_u32 s0, s0, 1
	s_lshl_b32 s1, s14, 8
	s_mul_i32 s0, s0, s1
	s_add_u32 s16, s12, s0
	s_addc_u32 s17, s13, 0
	s_add_u32 s18, s16, s14
	s_addc_u32 s19, s17, 0
	s_add_u32 s20, s18, s14
	s_addc_u32 s21, s19, 0
	s_add_u32 s22, s20, s14
	s_addc_u32 s23, s21, 0
	s_add_u32 s24, s22, s14
	s_addc_u32 s25, s23, 0
	s_add_u32 s26, s24, s14
	s_addc_u32 s27, s25, 0
	s_add_u32 s28, s26, s14
	s_addc_u32 s29, s27, 0
	s_add_u32 s30, s28, s14
	s_addc_u32 s31, s29, 0
	global_load_dwordx4 v[48:51], v4, s[16:17]
	global_load_dwordx4 v[52:55], v4, s[18:19]
	global_load_dwordx4 v[56:59], v4, s[20:21]
	global_load_dwordx4 v[60:63], v4, s[22:23]
	global_load_dwordx4 v[64:67], v4, s[24:25]
	global_load_dwordx4 v[68:71], v4, s[26:27]
	global_load_dwordx4 v[72:75], v4, s[28:29]
	global_load_dwordx4 v[76:79], v4, s[30:31]
	s_waitcnt vmcnt(8)
	v_cvt_pk_bf16_f32 v80, v16, v20
	v_cvt_pk_bf16_f32 v81, v24, v28
	v_cvt_pk_bf16_f32 v82, v32, v36
	v_cvt_pk_bf16_f32 v83, v40, v44
	v_cvt_pk_bf16_f32 v84, v17, v21
	v_cvt_pk_bf16_f32 v85, v25, v29
	v_cvt_pk_bf16_f32 v86, v33, v37
	v_cvt_pk_bf16_f32 v87, v41, v45
	v_cvt_pk_bf16_f32 v88, v18, v22
	v_cvt_pk_bf16_f32 v89, v26, v30
	v_cvt_pk_bf16_f32 v90, v34, v38
	v_cvt_pk_bf16_f32 v91, v42, v46
	v_cvt_pk_bf16_f32 v92, v19, v23
	v_cvt_pk_bf16_f32 v93, v27, v31
	v_cvt_pk_bf16_f32 v94, v35, v39
	v_cvt_pk_bf16_f32 v95, v43, v47
	s_sub_u32 s0, s8, 1
	s_min_u32 s0, s0, 2
	s_lshl_b32 s1, s14, 8
	s_mul_i32 s0, s0, s1
	s_add_u32 s16, s12, s0
	s_addc_u32 s17, s13, 0
	s_add_u32 s18, s16, s14
	s_addc_u32 s19, s17, 0
	s_add_u32 s20, s18, s14
	s_addc_u32 s21, s19, 0
	s_add_u32 s22, s20, s14
	s_addc_u32 s23, s21, 0
	s_add_u32 s24, s22, s14
	s_addc_u32 s25, s23, 0
	s_add_u32 s26, s24, s14
	s_addc_u32 s27, s25, 0
	s_add_u32 s28, s26, s14
	s_addc_u32 s29, s27, 0
	s_add_u32 s30, s28, s14
	s_addc_u32 s31, s29, 0
	global_load_dwordx4 v[16:19], v4, s[16:17]
	global_load_dwordx4 v[20:23], v4, s[18:19]
	global_load_dwordx4 v[24:27], v4, s[20:21]
	global_load_dwordx4 v[28:31], v4, s[22:23]
	global_load_dwordx4 v[32:35], v4, s[24:25]
	global_load_dwordx4 v[36:39], v4, s[26:27]
	global_load_dwordx4 v[40:43], v4, s[28:29]
	global_load_dwordx4 v[44:47], v4, s[30:31]
	ds_write_b128 v6, v[80:83] offset:0
	ds_write_b128 v6, v[84:87] offset:512
	ds_write_b128 v6, v[88:91] offset:1024
	ds_write_b128 v6, v[92:95] offset:1536
	s_waitcnt lgkmcnt(0)
	s_barrier
	ds_read_b128 v[96:99], v7
	ds_read_b128 v[100:103], v8
	ds_read_b128 v[104:107], v9
	ds_read_b128 v[108:111], v10
	s_cmp_gt_u32 s8, 0
	s_cbranch_scc0 .Lp0_n_skipst0
	s_waitcnt lgkmcnt(3)
	global_store_dwordx4 v5, v[96:99], s[34:35] sc1
	s_waitcnt lgkmcnt(2)
	global_store_dwordx4 v5, v[100:103], s[34:35] offset:128 sc1
	s_bitcmp1_b32 s9, 1
	s_cbranch_scc1 .Lp0_n_skipst0
	s_waitcnt lgkmcnt(1)
	global_store_dwordx4 v5, v[104:107], s[34:35] offset:256 sc1
	s_waitcnt lgkmcnt(0)
	global_store_dwordx4 v5, v[108:111], s[34:35] offset:384 sc1
.Lp0_n_skipst0:
	s_waitcnt lgkmcnt(0)
	s_waitcnt vmcnt(8)
	v_cvt_pk_bf16_f32 v80, v48, v52
	v_cvt_pk_bf16_f32 v81, v56, v60
	v_cvt_pk_bf16_f32 v82, v64, v68
	v_cvt_pk_bf16_f32 v83, v72, v76
	v_cvt_pk_bf16_f32 v84, v49, v53
	v_cvt_pk_bf16_f32 v85, v57, v61
	v_cvt_pk_bf16_f32 v86, v65, v69
	v_cvt_pk_bf16_f32 v87, v73, v77
	v_cvt_pk_bf16_f32 v88, v50, v54
	v_cvt_pk_bf16_f32 v89, v58, v62
	v_cvt_pk_bf16_f32 v90, v66, v70
	v_cvt_pk_bf16_f32 v91, v74, v78
	v_cvt_pk_bf16_f32 v92, v51, v55
	v_cvt_pk_bf16_f32 v93, v59, v63
	v_cvt_pk_bf16_f32 v94, v67, v71
	v_cvt_pk_bf16_f32 v95, v75, v79
	s_sub_u32 s0, s8, 1
	s_min_u32 s0, s0, 3
	s_lshl_b32 s1, s14, 8
	s_mul_i32 s0, s0, s1
	s_add_u32 s16, s12, s0
	s_addc_u32 s17, s13, 0
	s_add_u32 s18, s16, s14
	s_addc_u32 s19, s17, 0
	s_add_u32 s20, s18, s14
	s_addc_u32 s21, s19, 0
	s_add_u32 s22, s20, s14
	s_addc_u32 s23, s21, 0
	s_add_u32 s24, s22, s14
	s_addc_u32 s25, s23, 0
	s_add_u32 s26, s24, s14
	s_addc_u32 s27, s25, 0
	s_add_u32 s28, s26, s14
	s_addc_u32 s29, s27, 0
	s_add_u32 s30, s28, s14
	s_addc_u32 s31, s29, 0
	global_load_dwordx4 v[48:51], v4, s[16:17]
	global_load_dwordx4 v[52:55], v4, s[18:19]
	global_load_dwordx4 v[56:59], v4, s[20:21]
	global_load_dwordx4 v[60:63], v4, s[22:23]
	global_load_dwordx4 v[64:67], v4, s[24:25]
	global_load_dwordx4 v[68:71], v4, s[26:27]
	global_load_dwordx4 v[72:75], v4, s[28:29]
	global_load_dwordx4 v[76:79], v4, s[30:31]
	ds_write_b128 v6, v[80:83] offset:32768
	ds_write_b128 v6, v[84:87] offset:33280
	ds_write_b128 v6, v[88:91] offset:33792
	ds_write_b128 v6, v[92:95] offset:34304
	s_waitcnt lgkmcnt(0)
	s_barrier
	ds_read_b128 v[96:99], v7 offset:32768
	ds_read_b128 v[100:103], v8 offset:32768
	ds_read_b128 v[104:107], v9 offset:32768
	ds_read_b128 v[108:111], v10 offset:32768
	s_cmp_gt_u32 s8, 1
	s_cbranch_scc0 .Lp0_n_skipst1
	s_waitcnt lgkmcnt(3)
	global_store_dwordx4 v5, v[96:99], s[34:35] offset:512 sc1
	s_waitcnt lgkmcnt(2)
	global_store_dwordx4 v5, v[100:103], s[34:35] offset:640 sc1
	s_bitcmp1_b32 s9, 1
	s_cbranch_scc1 .Lp0_n_skipst1
	s_waitcnt lgkmcnt(1)
	global_store_dwordx4 v5, v[104:107], s[34:35] offset:768 sc1
	s_waitcnt lgkmcnt(0)
	global_store_dwordx4 v5, v[108:111], s[34:35] offset:896 sc1
.Lp0_n_skipst1:
	s_waitcnt lgkmcnt(0)
	s_waitcnt vmcnt(8)
	v_cvt_pk_bf16_f32 v80, v16, v20
	v_cvt_pk_bf16_f32 v81, v24, v28
	v_cvt_pk_bf16_f32 v82, v32, v36
	v_cvt_pk_bf16_f32 v83, v40, v44
	v_cvt_pk_bf16_f32 v84, v17, v21
	v_cvt_pk_bf16_f32 v85, v25, v29
	v_cvt_pk_bf16_f32 v86, v33, v37
	v_cvt_pk_bf16_f32 v87, v41, v45
	v_cvt_pk_bf16_f32 v88, v18, v22
	v_cvt_pk_bf16_f32 v89, v26, v30
	v_cvt_pk_bf16_f32 v90, v34, v38
	v_cvt_pk_bf16_f32 v91, v42, v46
	v_cvt_pk_bf16_f32 v92, v19, v23
	v_cvt_pk_bf16_f32 v93, v27, v31
	v_cvt_pk_bf16_f32 v94, v35, v39
	v_cvt_pk_bf16_f32 v95, v43, v47
	ds_write_b128 v6, v[80:83] offset:0
	ds_write_b128 v6, v[84:87] offset:512
	ds_write_b128 v6, v[88:91] offset:1024
	ds_write_b128 v6, v[92:95] offset:1536
	s_waitcnt lgkmcnt(0)
	s_barrier
	ds_read_b128 v[96:99], v7
	ds_read_b128 v[100:103], v8
	ds_read_b128 v[104:107], v9
	ds_read_b128 v[108:111], v10
	s_cmp_gt_u32 s8, 2
	s_cbranch_scc0 .Lp0_n_skipst2
	s_waitcnt lgkmcnt(3)
	global_store_dwordx4 v5, v[96:99], s[34:35] offset:1024 sc1
	s_waitcnt lgkmcnt(2)
	global_store_dwordx4 v5, v[100:103], s[34:35] offset:1152 sc1
	s_bitcmp1_b32 s9, 1
	s_cbranch_scc1 .Lp0_n_skipst2
	s_waitcnt lgkmcnt(1)
	global_store_dwordx4 v5, v[104:107], s[34:35] offset:1280 sc1
	s_waitcnt lgkmcnt(0)
	global_store_dwordx4 v5, v[108:111], s[34:35] offset:1408 sc1
.Lp0_n_skipst2:
	s_waitcnt lgkmcnt(0)
	s_waitcnt vmcnt(0)
	v_cvt_pk_bf16_f32 v80, v48, v52
	v_cvt_pk_bf16_f32 v81, v56, v60
	v_cvt_pk_bf16_f32 v82, v64, v68
	v_cvt_pk_bf16_f32 v83, v72, v76
	v_cvt_pk_bf16_f32 v84, v49, v53
	v_cvt_pk_bf16_f32 v85, v57, v61
	v_cvt_pk_bf16_f32 v86, v65, v69
	v_cvt_pk_bf16_f32 v87, v73, v77
	v_cvt_pk_bf16_f32 v88, v50, v54
	v_cvt_pk_bf16_f32 v89, v58, v62
	v_cvt_pk_bf16_f32 v90, v66, v70
	v_cvt_pk_bf16_f32 v91, v74, v78
	v_cvt_pk_bf16_f32 v92, v51, v55
	v_cvt_pk_bf16_f32 v93, v59, v63
	v_cvt_pk_bf16_f32 v94, v67, v71
	v_cvt_pk_bf16_f32 v95, v75, v79
	ds_write_b128 v6, v[80:83] offset:32768
	ds_write_b128 v6, v[84:87] offset:33280
	ds_write_b128 v6, v[88:91] offset:33792
	ds_write_b128 v6, v[92:95] offset:34304
	s_waitcnt lgkmcnt(0)
	s_barrier
	ds_read_b128 v[96:99], v7 offset:32768
	ds_read_b128 v[100:103], v8 offset:32768
	ds_read_b128 v[104:107], v9 offset:32768
	ds_read_b128 v[108:111], v10 offset:32768
	s_cmp_gt_u32 s8, 3
	s_cbranch_scc0 .Lp0_n_skipst3
	s_waitcnt lgkmcnt(3)
	global_store_dwordx4 v5, v[96:99], s[34:35] offset:1536 sc1
	s_waitcnt lgkmcnt(2)
	global_store_dwordx4 v5, v[100:103], s[34:35] offset:1664 sc1
	s_bitcmp1_b32 s9, 1
	s_cbranch_scc1 .Lp0_n_skipst3
	s_waitcnt lgkmcnt(1)
	global_store_dwordx4 v5, v[104:107], s[34:35] offset:1792 sc1
	s_waitcnt lgkmcnt(0)
	global_store_dwordx4 v5, v[108:111], s[34:35] offset:1920 sc1

.Lp0_gate:
	s_mov_b32 s16, s12
	s_mov_b32 s17, s13
	s_add_u32 s18, s16, s14
	s_addc_u32 s19, s17, 0
	s_add_u32 s20, s18, s14
	s_addc_u32 s21, s19, 0
	s_add_u32 s22, s20, s14
	s_addc_u32 s23, s21, 0
	s_add_u32 s24, s22, s14
	s_addc_u32 s25, s23, 0
	s_add_u32 s26, s24, s14
	s_addc_u32 s27, s25, 0
	s_add_u32 s28, s26, s14
	s_addc_u32 s29, s27, 0
	s_add_u32 s30, s28, s14
	s_addc_u32 s31, s29, 0
	global_load_dwordx4 v[16:19], v4, s[16:17]
	global_load_dwordx4 v[20:23], v4, s[18:19]
	global_load_dwordx4 v[24:27], v4, s[20:21]
	global_load_dwordx4 v[28:31], v4, s[22:23]
	global_load_dwordx4 v[32:35], v4, s[24:25]
	global_load_dwordx4 v[36:39], v4, s[26:27]
	global_load_dwordx4 v[40:43], v4, s[28:29]
	global_load_dwordx4 v[44:47], v4, s[30:31]
	global_load_dwordx4 v[112:115], v11, s[38:39] offset:0
	global_load_dwordx4 v[116:119], v11, s[38:39] offset:16
	global_load_dwordx4 v[120:123], v11, s[40:41] offset:0
	global_load_dwordx4 v[124:127], v11, s[40:41] offset:16
	s_sub_u32 s0, s8, 1
	s_min_u32 s0, s0, 1
	s_lshl_b32 s1, s14, 8
	s_mul_i32 s0, s0, s1
	s_add_u32 s16, s12, s0
	s_addc_u32 s17, s13, 0
	s_add_u32 s18, s16, s14
	s_addc_u32 s19, s17, 0
	s_add_u32 s20, s18, s14
	s_addc_u32 s21, s19, 0
	s_add_u32 s22, s20, s14
	s_addc_u32 s23, s21, 0
	s_add_u32 s24, s22, s14
	s_addc_u32 s25, s23, 0
	s_add_u32 s26, s24, s14
	s_addc_u32 s27, s25, 0
	s_add_u32 s28, s26, s14
	s_addc_u32 s29, s27, 0
	s_add_u32 s30, s28, s14
	s_addc_u32 s31, s29, 0
	global_load_dwordx4 v[48:51], v4, s[16:17]
	global_load_dwordx4 v[52:55], v4, s[18:19]
	global_load_dwordx4 v[56:59], v4, s[20:21]
	global_load_dwordx4 v[60:63], v4, s[22:23]
	global_load_dwordx4 v[64:67], v4, s[24:25]
	global_load_dwordx4 v[68:71], v4, s[26:27]
	global_load_dwordx4 v[72:75], v4, s[28:29]
	global_load_dwordx4 v[76:79], v4, s[30:31]
	global_load_dwordx4 v[128:131], v11, s[38:39] offset:1024
	global_load_dwordx4 v[132:135], v11, s[38:39] offset:1040
	global_load_dwordx4 v[136:139], v11, s[40:41] offset:1024
	global_load_dwordx4 v[140:143], v11, s[40:41] offset:1040
	s_waitcnt vmcnt(12)
	v_fmac_f32_e32 v148, v120, v16
	v_fmac_f32_e32 v148, v121, v20
	v_fmac_f32_e32 v148, v122, v24
	v_fmac_f32_e32 v148, v123, v28
	v_fmac_f32_e32 v148, v124, v32
	v_fmac_f32_e32 v148, v125, v36
	v_fmac_f32_e32 v148, v126, v40
	v_fmac_f32_e32 v148, v127, v44
	v_fmac_f32_e32 v149, v120, v17
	v_fmac_f32_e32 v149, v121, v21
	v_fmac_f32_e32 v149, v122, v25
	v_fmac_f32_e32 v149, v123, v29
	v_fmac_f32_e32 v149, v124, v33
	v_fmac_f32_e32 v149, v125, v37
	v_fmac_f32_e32 v149, v126, v41
	v_fmac_f32_e32 v149, v127, v45
	v_fmac_f32_e32 v150, v120, v18
	v_fmac_f32_e32 v150, v121, v22
	v_fmac_f32_e32 v150, v122, v26
	v_fmac_f32_e32 v150, v123, v30
	v_fmac_f32_e32 v150, v124, v34
	v_fmac_f32_e32 v150, v125, v38
	v_fmac_f32_e32 v150, v126, v42
	v_fmac_f32_e32 v150, v127, v46
	v_fmac_f32_e32 v151, v120, v19
	v_fmac_f32_e32 v151, v121, v23
	v_fmac_f32_e32 v151, v122, v27
	v_fmac_f32_e32 v151, v123, v31
	v_fmac_f32_e32 v151, v124, v35
	v_fmac_f32_e32 v151, v125, v39
	v_fmac_f32_e32 v151, v126, v43
	v_fmac_f32_e32 v151, v127, v47
	v_mul_f32_e32 v16, v112, v16
	v_mul_f32_e32 v17, v112, v17
	v_mul_f32_e32 v18, v112, v18
	v_mul_f32_e32 v19, v112, v19
	v_mul_f32_e32 v20, v113, v20
	v_mul_f32_e32 v21, v113, v21
	v_mul_f32_e32 v22, v113, v22
	v_mul_f32_e32 v23, v113, v23
	v_mul_f32_e32 v24, v114, v24
	v_mul_f32_e32 v25, v114, v25
	v_mul_f32_e32 v26, v114, v26
	v_mul_f32_e32 v27, v114, v27
	v_mul_f32_e32 v28, v115, v28
	v_mul_f32_e32 v29, v115, v29
	v_mul_f32_e32 v30, v115, v30
	v_mul_f32_e32 v31, v115, v31
	v_mul_f32_e32 v32, v116, v32
	v_mul_f32_e32 v33, v116, v33
	v_mul_f32_e32 v34, v116, v34
	v_mul_f32_e32 v35, v116, v35
	v_mul_f32_e32 v36, v117, v36
	v_mul_f32_e32 v37, v117, v37
	v_mul_f32_e32 v38, v117, v38
	v_mul_f32_e32 v39, v117, v39
	v_mul_f32_e32 v40, v118, v40
	v_mul_f32_e32 v41, v118, v41
	v_mul_f32_e32 v42, v118, v42
	v_mul_f32_e32 v43, v118, v43
	v_mul_f32_e32 v44, v119, v44
	v_mul_f32_e32 v45, v119, v45
	v_mul_f32_e32 v46, v119, v46
	v_mul_f32_e32 v47, v119, v47
	v_cvt_pk_bf16_f32 v80, v16, v20
	v_cvt_pk_bf16_f32 v81, v24, v28
	v_cvt_pk_bf16_f32 v82, v32, v36
	v_cvt_pk_bf16_f32 v83, v40, v44
	v_cvt_pk_bf16_f32 v84, v17, v21
	v_cvt_pk_bf16_f32 v85, v25, v29
	v_cvt_pk_bf16_f32 v86, v33, v37
	v_cvt_pk_bf16_f32 v87, v41, v45
	v_cvt_pk_bf16_f32 v88, v18, v22
	v_cvt_pk_bf16_f32 v89, v26, v30
	v_cvt_pk_bf16_f32 v90, v34, v38
	v_cvt_pk_bf16_f32 v91, v42, v46
	v_cvt_pk_bf16_f32 v92, v19, v23
	v_cvt_pk_bf16_f32 v93, v27, v31
	v_cvt_pk_bf16_f32 v94, v35, v39
	v_cvt_pk_bf16_f32 v95, v43, v47
	v_lshlrev_b32_e32 v152, 16, v80
	v_and_b32_e32 v153, 0xffff0000, v80
	v_add_f32_e32 v144, v144, v152
	v_add_f32_e32 v144, v144, v153
	v_lshlrev_b32_e32 v152, 16, v81
	v_and_b32_e32 v153, 0xffff0000, v81
	v_add_f32_e32 v144, v144, v152
	v_add_f32_e32 v144, v144, v153
	v_lshlrev_b32_e32 v152, 16, v82
	v_and_b32_e32 v153, 0xffff0000, v82
	v_add_f32_e32 v144, v144, v152
	v_add_f32_e32 v144, v144, v153
	v_lshlrev_b32_e32 v152, 16, v83
	v_and_b32_e32 v153, 0xffff0000, v83
	v_add_f32_e32 v144, v144, v152
	v_add_f32_e32 v144, v144, v153
	v_lshlrev_b32_e32 v152, 16, v84
	v_and_b32_e32 v153, 0xffff0000, v84
	v_add_f32_e32 v145, v145, v152
	v_add_f32_e32 v145, v145, v153
	v_lshlrev_b32_e32 v152, 16, v85
	v_and_b32_e32 v153, 0xffff0000, v85
	v_add_f32_e32 v145, v145, v152
	v_add_f32_e32 v145, v145, v153
	v_lshlrev_b32_e32 v152, 16, v86
	v_and_b32_e32 v153, 0xffff0000, v86
	v_add_f32_e32 v145, v145, v152
	v_add_f32_e32 v145, v145, v153
	v_lshlrev_b32_e32 v152, 16, v87
	v_and_b32_e32 v153, 0xffff0000, v87
	v_add_f32_e32 v145, v145, v152
	v_add_f32_e32 v145, v145, v153
	v_lshlrev_b32_e32 v152, 16, v88
	v_and_b32_e32 v153, 0xffff0000, v88
	v_add_f32_e32 v146, v146, v152
	v_add_f32_e32 v146, v146, v153
	v_lshlrev_b32_e32 v152, 16, v89
	v_and_b32_e32 v153, 0xffff0000, v89
	v_add_f32_e32 v146, v146, v152
	v_add_f32_e32 v146, v146, v153
	v_lshlrev_b32_e32 v152, 16, v90
	v_and_b32_e32 v153, 0xffff0000, v90
	v_add_f32_e32 v146, v146, v152
	v_add_f32_e32 v146, v146, v153
	v_lshlrev_b32_e32 v152, 16, v91
	v_and_b32_e32 v153, 0xffff0000, v91
	v_add_f32_e32 v146, v146, v152
	v_add_f32_e32 v146, v146, v153
	v_lshlrev_b32_e32 v152, 16, v92
	v_and_b32_e32 v153, 0xffff0000, v92
	v_add_f32_e32 v147, v147, v152
	v_add_f32_e32 v147, v147, v153
	v_lshlrev_b32_e32 v152, 16, v93
	v_and_b32_e32 v153, 0xffff0000, v93
	v_add_f32_e32 v147, v147, v152
	v_add_f32_e32 v147, v147, v153
	v_lshlrev_b32_e32 v152, 16, v94
	v_and_b32_e32 v153, 0xffff0000, v94
	v_add_f32_e32 v147, v147, v152
	v_add_f32_e32 v147, v147, v153
	v_lshlrev_b32_e32 v152, 16, v95
	v_and_b32_e32 v153, 0xffff0000, v95
	v_add_f32_e32 v147, v147, v152
	v_add_f32_e32 v147, v147, v153
	s_sub_u32 s0, s8, 1
	s_min_u32 s0, s0, 2
	s_lshl_b32 s1, s14, 8
	s_mul_i32 s0, s0, s1
	s_add_u32 s16, s12, s0
	s_addc_u32 s17, s13, 0
	s_add_u32 s18, s16, s14
	s_addc_u32 s19, s17, 0
	s_add_u32 s20, s18, s14
	s_addc_u32 s21, s19, 0
	s_add_u32 s22, s20, s14
	s_addc_u32 s23, s21, 0
	s_add_u32 s24, s22, s14
	s_addc_u32 s25, s23, 0
	s_add_u32 s26, s24, s14
	s_addc_u32 s27, s25, 0
	s_add_u32 s28, s26, s14
	s_addc_u32 s29, s27, 0
	s_add_u32 s30, s28, s14
	s_addc_u32 s31, s29, 0
	global_load_dwordx4 v[16:19], v4, s[16:17]
	global_load_dwordx4 v[20:23], v4, s[18:19]
	global_load_dwordx4 v[24:27], v4, s[20:21]
	global_load_dwordx4 v[28:31], v4, s[22:23]
	global_load_dwordx4 v[32:35], v4, s[24:25]
	global_load_dwordx4 v[36:39], v4, s[26:27]
	global_load_dwordx4 v[40:43], v4, s[28:29]
	global_load_dwordx4 v[44:47], v4, s[30:31]
	global_load_dwordx4 v[112:115], v11, s[38:39] offset:2048
	global_load_dwordx4 v[116:119], v11, s[38:39] offset:2064
	global_load_dwordx4 v[120:123], v11, s[40:41] offset:2048
	global_load_dwordx4 v[124:127], v11, s[40:41] offset:2064
	ds_write_b128 v6, v[80:83] offset:0
	ds_write_b128 v6, v[84:87] offset:512
	ds_write_b128 v6, v[88:91] offset:1024
	ds_write_b128 v6, v[92:95] offset:1536
	s_waitcnt lgkmcnt(0)
	s_barrier
	ds_read_b128 v[96:99], v7
	ds_read_b128 v[100:103], v8
	ds_read_b128 v[104:107], v9
	ds_read_b128 v[108:111], v10
	s_cmp_gt_u32 s8, 0
	s_cbranch_scc0 .Lp0_g_skipst0
	s_waitcnt lgkmcnt(3)
	global_store_dwordx4 v5, v[96:99], s[34:35] sc1
	s_waitcnt lgkmcnt(2)
	global_store_dwordx4 v5, v[100:103], s[34:35] offset:128 sc1
	s_bitcmp1_b32 s9, 1
	s_cbranch_scc1 .Lp0_g_skipst0
	s_waitcnt lgkmcnt(1)
	global_store_dwordx4 v5, v[104:107], s[34:35] offset:256 sc1
	s_waitcnt lgkmcnt(0)
	global_store_dwordx4 v5, v[108:111], s[34:35] offset:384 sc1
.Lp0_g_skipst0:
	s_waitcnt lgkmcnt(0)
	s_waitcnt vmcnt(12)
	v_fmac_f32_e32 v148, v136, v48
	v_fmac_f32_e32 v148, v137, v52
	v_fmac_f32_e32 v148, v138, v56
	v_fmac_f32_e32 v148, v139, v60
	v_fmac_f32_e32 v148, v140, v64
	v_fmac_f32_e32 v148, v141, v68
	v_fmac_f32_e32 v148, v142, v72
	v_fmac_f32_e32 v148, v143, v76
	v_fmac_f32_e32 v149, v136, v49
	v_fmac_f32_e32 v149, v137, v53
	v_fmac_f32_e32 v149, v138, v57
	v_fmac_f32_e32 v149, v139, v61
	v_fmac_f32_e32 v149, v140, v65
	v_fmac_f32_e32 v149, v141, v69
	v_fmac_f32_e32 v149, v142, v73
	v_fmac_f32_e32 v149, v143, v77
	v_fmac_f32_e32 v150, v136, v50
	v_fmac_f32_e32 v150, v137, v54
	v_fmac_f32_e32 v150, v138, v58
	v_fmac_f32_e32 v150, v139, v62
	v_fmac_f32_e32 v150, v140, v66
	v_fmac_f32_e32 v150, v141, v70
	v_fmac_f32_e32 v150, v142, v74
	v_fmac_f32_e32 v150, v143, v78
	v_fmac_f32_e32 v151, v136, v51
	v_fmac_f32_e32 v151, v137, v55
	v_fmac_f32_e32 v151, v138, v59
	v_fmac_f32_e32 v151, v139, v63
	v_fmac_f32_e32 v151, v140, v67
	v_fmac_f32_e32 v151, v141, v71
	v_fmac_f32_e32 v151, v142, v75
	v_fmac_f32_e32 v151, v143, v79
	v_mul_f32_e32 v48, v128, v48
	v_mul_f32_e32 v49, v128, v49
	v_mul_f32_e32 v50, v128, v50
	v_mul_f32_e32 v51, v128, v51
	v_mul_f32_e32 v52, v129, v52
	v_mul_f32_e32 v53, v129, v53
	v_mul_f32_e32 v54, v129, v54
	v_mul_f32_e32 v55, v129, v55
	v_mul_f32_e32 v56, v130, v56
	v_mul_f32_e32 v57, v130, v57
	v_mul_f32_e32 v58, v130, v58
	v_mul_f32_e32 v59, v130, v59
	v_mul_f32_e32 v60, v131, v60
	v_mul_f32_e32 v61, v131, v61
	v_mul_f32_e32 v62, v131, v62
	v_mul_f32_e32 v63, v131, v63
	v_mul_f32_e32 v64, v132, v64
	v_mul_f32_e32 v65, v132, v65
	v_mul_f32_e32 v66, v132, v66
	v_mul_f32_e32 v67, v132, v67
	v_mul_f32_e32 v68, v133, v68
	v_mul_f32_e32 v69, v133, v69
	v_mul_f32_e32 v70, v133, v70
	v_mul_f32_e32 v71, v133, v71
	v_mul_f32_e32 v72, v134, v72
	v_mul_f32_e32 v73, v134, v73
	v_mul_f32_e32 v74, v134, v74
	v_mul_f32_e32 v75, v134, v75
	v_mul_f32_e32 v76, v135, v76
	v_mul_f32_e32 v77, v135, v77
	v_mul_f32_e32 v78, v135, v78
	v_mul_f32_e32 v79, v135, v79
	v_cvt_pk_bf16_f32 v80, v48, v52
	v_cvt_pk_bf16_f32 v81, v56, v60
	v_cvt_pk_bf16_f32 v82, v64, v68
	v_cvt_pk_bf16_f32 v83, v72, v76
	v_cvt_pk_bf16_f32 v84, v49, v53
	v_cvt_pk_bf16_f32 v85, v57, v61
	v_cvt_pk_bf16_f32 v86, v65, v69
	v_cvt_pk_bf16_f32 v87, v73, v77
	v_cvt_pk_bf16_f32 v88, v50, v54
	v_cvt_pk_bf16_f32 v89, v58, v62
	v_cvt_pk_bf16_f32 v90, v66, v70
	v_cvt_pk_bf16_f32 v91, v74, v78
	v_cvt_pk_bf16_f32 v92, v51, v55
	v_cvt_pk_bf16_f32 v93, v59, v63
	v_cvt_pk_bf16_f32 v94, v67, v71
	v_cvt_pk_bf16_f32 v95, v75, v79
	v_lshlrev_b32_e32 v152, 16, v80
	v_and_b32_e32 v153, 0xffff0000, v80
	v_add_f32_e32 v144, v144, v152
	v_add_f32_e32 v144, v144, v153
	v_lshlrev_b32_e32 v152, 16, v81
	v_and_b32_e32 v153, 0xffff0000, v81
	v_add_f32_e32 v144, v144, v152
	v_add_f32_e32 v144, v144, v153
	v_lshlrev_b32_e32 v152, 16, v82
	v_and_b32_e32 v153, 0xffff0000, v82
	v_add_f32_e32 v144, v144, v152
	v_add_f32_e32 v144, v144, v153
	v_lshlrev_b32_e32 v152, 16, v83
	v_and_b32_e32 v153, 0xffff0000, v83
	v_add_f32_e32 v144, v144, v152
	v_add_f32_e32 v144, v144, v153
	v_lshlrev_b32_e32 v152, 16, v84
	v_and_b32_e32 v153, 0xffff0000, v84
	v_add_f32_e32 v145, v145, v152
	v_add_f32_e32 v145, v145, v153
	v_lshlrev_b32_e32 v152, 16, v85
	v_and_b32_e32 v153, 0xffff0000, v85
	v_add_f32_e32 v145, v145, v152
	v_add_f32_e32 v145, v145, v153
	v_lshlrev_b32_e32 v152, 16, v86
	v_and_b32_e32 v153, 0xffff0000, v86
	v_add_f32_e32 v145, v145, v152
	v_add_f32_e32 v145, v145, v153
	v_lshlrev_b32_e32 v152, 16, v87
	v_and_b32_e32 v153, 0xffff0000, v87
	v_add_f32_e32 v145, v145, v152
	v_add_f32_e32 v145, v145, v153
	v_lshlrev_b32_e32 v152, 16, v88
	v_and_b32_e32 v153, 0xffff0000, v88
	v_add_f32_e32 v146, v146, v152
	v_add_f32_e32 v146, v146, v153
	v_lshlrev_b32_e32 v152, 16, v89
	v_and_b32_e32 v153, 0xffff0000, v89
	v_add_f32_e32 v146, v146, v152
	v_add_f32_e32 v146, v146, v153
	v_lshlrev_b32_e32 v152, 16, v90
	v_and_b32_e32 v153, 0xffff0000, v90
	v_add_f32_e32 v146, v146, v152
	v_add_f32_e32 v146, v146, v153
	v_lshlrev_b32_e32 v152, 16, v91
	v_and_b32_e32 v153, 0xffff0000, v91
	v_add_f32_e32 v146, v146, v152
	v_add_f32_e32 v146, v146, v153
	v_lshlrev_b32_e32 v152, 16, v92
	v_and_b32_e32 v153, 0xffff0000, v92
	v_add_f32_e32 v147, v147, v152
	v_add_f32_e32 v147, v147, v153
	v_lshlrev_b32_e32 v152, 16, v93
	v_and_b32_e32 v153, 0xffff0000, v93
	v_add_f32_e32 v147, v147, v152
	v_add_f32_e32 v147, v147, v153
	v_lshlrev_b32_e32 v152, 16, v94
	v_and_b32_e32 v153, 0xffff0000, v94
	v_add_f32_e32 v147, v147, v152
	v_add_f32_e32 v147, v147, v153
	v_lshlrev_b32_e32 v152, 16, v95
	v_and_b32_e32 v153, 0xffff0000, v95
	v_add_f32_e32 v147, v147, v152
	v_add_f32_e32 v147, v147, v153
	s_sub_u32 s0, s8, 1
	s_min_u32 s0, s0, 3
	s_lshl_b32 s1, s14, 8
	s_mul_i32 s0, s0, s1
	s_add_u32 s16, s12, s0
	s_addc_u32 s17, s13, 0
	s_add_u32 s18, s16, s14
	s_addc_u32 s19, s17, 0
	s_add_u32 s20, s18, s14
	s_addc_u32 s21, s19, 0
	s_add_u32 s22, s20, s14
	s_addc_u32 s23, s21, 0
	s_add_u32 s24, s22, s14
	s_addc_u32 s25, s23, 0
	s_add_u32 s26, s24, s14
	s_addc_u32 s27, s25, 0
	s_add_u32 s28, s26, s14
	s_addc_u32 s29, s27, 0
	s_add_u32 s30, s28, s14
	s_addc_u32 s31, s29, 0
	global_load_dwordx4 v[48:51], v4, s[16:17]
	global_load_dwordx4 v[52:55], v4, s[18:19]
	global_load_dwordx4 v[56:59], v4, s[20:21]
	global_load_dwordx4 v[60:63], v4, s[22:23]
	global_load_dwordx4 v[64:67], v4, s[24:25]
	global_load_dwordx4 v[68:71], v4, s[26:27]
	global_load_dwordx4 v[72:75], v4, s[28:29]
	global_load_dwordx4 v[76:79], v4, s[30:31]
	global_load_dwordx4 v[128:131], v11, s[38:39] offset:3072
	global_load_dwordx4 v[132:135], v11, s[38:39] offset:3088
	global_load_dwordx4 v[136:139], v11, s[40:41] offset:3072
	global_load_dwordx4 v[140:143], v11, s[40:41] offset:3088
	ds_write_b128 v6, v[80:83] offset:32768
	ds_write_b128 v6, v[84:87] offset:33280
	ds_write_b128 v6, v[88:91] offset:33792
	ds_write_b128 v6, v[92:95] offset:34304
	s_waitcnt lgkmcnt(0)
	s_barrier
	ds_read_b128 v[96:99], v7 offset:32768
	ds_read_b128 v[100:103], v8 offset:32768
	ds_read_b128 v[104:107], v9 offset:32768
	ds_read_b128 v[108:111], v10 offset:32768
	s_cmp_gt_u32 s8, 1
	s_cbranch_scc0 .Lp0_g_skipst1
	s_waitcnt lgkmcnt(3)
	global_store_dwordx4 v5, v[96:99], s[34:35] offset:512 sc1
	s_waitcnt lgkmcnt(2)
	global_store_dwordx4 v5, v[100:103], s[34:35] offset:640 sc1
	s_bitcmp1_b32 s9, 1
	s_cbranch_scc1 .Lp0_g_skipst1
	s_waitcnt lgkmcnt(1)
	global_store_dwordx4 v5, v[104:107], s[34:35] offset:768 sc1
	s_waitcnt lgkmcnt(0)
	global_store_dwordx4 v5, v[108:111], s[34:35] offset:896 sc1
.Lp0_g_skipst1:
	s_waitcnt lgkmcnt(0)
	s_waitcnt vmcnt(12)
	v_fmac_f32_e32 v148, v120, v16
	v_fmac_f32_e32 v148, v121, v20
	v_fmac_f32_e32 v148, v122, v24
	v_fmac_f32_e32 v148, v123, v28
	v_fmac_f32_e32 v148, v124, v32
	v_fmac_f32_e32 v148, v125, v36
	v_fmac_f32_e32 v148, v126, v40
	v_fmac_f32_e32 v148, v127, v44
	v_fmac_f32_e32 v149, v120, v17
	v_fmac_f32_e32 v149, v121, v21
	v_fmac_f32_e32 v149, v122, v25
	v_fmac_f32_e32 v149, v123, v29
	v_fmac_f32_e32 v149, v124, v33
	v_fmac_f32_e32 v149, v125, v37
	v_fmac_f32_e32 v149, v126, v41
	v_fmac_f32_e32 v149, v127, v45
	v_fmac_f32_e32 v150, v120, v18
	v_fmac_f32_e32 v150, v121, v22
	v_fmac_f32_e32 v150, v122, v26
	v_fmac_f32_e32 v150, v123, v30
	v_fmac_f32_e32 v150, v124, v34
	v_fmac_f32_e32 v150, v125, v38
	v_fmac_f32_e32 v150, v126, v42
	v_fmac_f32_e32 v150, v127, v46
	v_fmac_f32_e32 v151, v120, v19
	v_fmac_f32_e32 v151, v121, v23
	v_fmac_f32_e32 v151, v122, v27
	v_fmac_f32_e32 v151, v123, v31
	v_fmac_f32_e32 v151, v124, v35
	v_fmac_f32_e32 v151, v125, v39
	v_fmac_f32_e32 v151, v126, v43
	v_fmac_f32_e32 v151, v127, v47
	v_mul_f32_e32 v16, v112, v16
	v_mul_f32_e32 v17, v112, v17
	v_mul_f32_e32 v18, v112, v18
	v_mul_f32_e32 v19, v112, v19
	v_mul_f32_e32 v20, v113, v20
	v_mul_f32_e32 v21, v113, v21
	v_mul_f32_e32 v22, v113, v22
	v_mul_f32_e32 v23, v113, v23
	v_mul_f32_e32 v24, v114, v24
	v_mul_f32_e32 v25, v114, v25
	v_mul_f32_e32 v26, v114, v26
	v_mul_f32_e32 v27, v114, v27
	v_mul_f32_e32 v28, v115, v28
	v_mul_f32_e32 v29, v115, v29
	v_mul_f32_e32 v30, v115, v30
	v_mul_f32_e32 v31, v115, v31
	v_mul_f32_e32 v32, v116, v32
	v_mul_f32_e32 v33, v116, v33
	v_mul_f32_e32 v34, v116, v34
	v_mul_f32_e32 v35, v116, v35
	v_mul_f32_e32 v36, v117, v36
	v_mul_f32_e32 v37, v117, v37
	v_mul_f32_e32 v38, v117, v38
	v_mul_f32_e32 v39, v117, v39
	v_mul_f32_e32 v40, v118, v40
	v_mul_f32_e32 v41, v118, v41
	v_mul_f32_e32 v42, v118, v42
	v_mul_f32_e32 v43, v118, v43
	v_mul_f32_e32 v44, v119, v44
	v_mul_f32_e32 v45, v119, v45
	v_mul_f32_e32 v46, v119, v46
	v_mul_f32_e32 v47, v119, v47
	v_cvt_pk_bf16_f32 v80, v16, v20
	v_cvt_pk_bf16_f32 v81, v24, v28
	v_cvt_pk_bf16_f32 v82, v32, v36
	v_cvt_pk_bf16_f32 v83, v40, v44
	v_cvt_pk_bf16_f32 v84, v17, v21
	v_cvt_pk_bf16_f32 v85, v25, v29
	v_cvt_pk_bf16_f32 v86, v33, v37
	v_cvt_pk_bf16_f32 v87, v41, v45
	v_cvt_pk_bf16_f32 v88, v18, v22
	v_cvt_pk_bf16_f32 v89, v26, v30
	v_cvt_pk_bf16_f32 v90, v34, v38
	v_cvt_pk_bf16_f32 v91, v42, v46
	v_cvt_pk_bf16_f32 v92, v19, v23
	v_cvt_pk_bf16_f32 v93, v27, v31
	v_cvt_pk_bf16_f32 v94, v35, v39
	v_cvt_pk_bf16_f32 v95, v43, v47
	v_lshlrev_b32_e32 v152, 16, v80
	v_and_b32_e32 v153, 0xffff0000, v80
	v_add_f32_e32 v144, v144, v152
	v_add_f32_e32 v144, v144, v153
	v_lshlrev_b32_e32 v152, 16, v81
	v_and_b32_e32 v153, 0xffff0000, v81
	v_add_f32_e32 v144, v144, v152
	v_add_f32_e32 v144, v144, v153
	v_lshlrev_b32_e32 v152, 16, v82
	v_and_b32_e32 v153, 0xffff0000, v82
	v_add_f32_e32 v144, v144, v152
	v_add_f32_e32 v144, v144, v153
	v_lshlrev_b32_e32 v152, 16, v83
	v_and_b32_e32 v153, 0xffff0000, v83
	v_add_f32_e32 v144, v144, v152
	v_add_f32_e32 v144, v144, v153
	v_lshlrev_b32_e32 v152, 16, v84
	v_and_b32_e32 v153, 0xffff0000, v84
	v_add_f32_e32 v145, v145, v152
	v_add_f32_e32 v145, v145, v153
	v_lshlrev_b32_e32 v152, 16, v85
	v_and_b32_e32 v153, 0xffff0000, v85
	v_add_f32_e32 v145, v145, v152
	v_add_f32_e32 v145, v145, v153
	v_lshlrev_b32_e32 v152, 16, v86
	v_and_b32_e32 v153, 0xffff0000, v86
	v_add_f32_e32 v145, v145, v152
	v_add_f32_e32 v145, v145, v153
	v_lshlrev_b32_e32 v152, 16, v87
	v_and_b32_e32 v153, 0xffff0000, v87
	v_add_f32_e32 v145, v145, v152
	v_add_f32_e32 v145, v145, v153
	v_lshlrev_b32_e32 v152, 16, v88
	v_and_b32_e32 v153, 0xffff0000, v88
	v_add_f32_e32 v146, v146, v152
	v_add_f32_e32 v146, v146, v153
	v_lshlrev_b32_e32 v152, 16, v89
	v_and_b32_e32 v153, 0xffff0000, v89
	v_add_f32_e32 v146, v146, v152
	v_add_f32_e32 v146, v146, v153
	v_lshlrev_b32_e32 v152, 16, v90
	v_and_b32_e32 v153, 0xffff0000, v90
	v_add_f32_e32 v146, v146, v152
	v_add_f32_e32 v146, v146, v153
	v_lshlrev_b32_e32 v152, 16, v91
	v_and_b32_e32 v153, 0xffff0000, v91
	v_add_f32_e32 v146, v146, v152
	v_add_f32_e32 v146, v146, v153
	v_lshlrev_b32_e32 v152, 16, v92
	v_and_b32_e32 v153, 0xffff0000, v92
	v_add_f32_e32 v147, v147, v152
	v_add_f32_e32 v147, v147, v153
	v_lshlrev_b32_e32 v152, 16, v93
	v_and_b32_e32 v153, 0xffff0000, v93
	v_add_f32_e32 v147, v147, v152
	v_add_f32_e32 v147, v147, v153
	v_lshlrev_b32_e32 v152, 16, v94
	v_and_b32_e32 v153, 0xffff0000, v94
	v_add_f32_e32 v147, v147, v152
	v_add_f32_e32 v147, v147, v153
	v_lshlrev_b32_e32 v152, 16, v95
	v_and_b32_e32 v153, 0xffff0000, v95
	v_add_f32_e32 v147, v147, v152
	v_add_f32_e32 v147, v147, v153
	ds_write_b128 v6, v[80:83] offset:0
	ds_write_b128 v6, v[84:87] offset:512
	ds_write_b128 v6, v[88:91] offset:1024
	ds_write_b128 v6, v[92:95] offset:1536
	s_waitcnt lgkmcnt(0)
	s_barrier
	ds_read_b128 v[96:99], v7
	ds_read_b128 v[100:103], v8
	ds_read_b128 v[104:107], v9
	ds_read_b128 v[108:111], v10
	s_cmp_gt_u32 s8, 2
	s_cbranch_scc0 .Lp0_g_skipst2
	s_waitcnt lgkmcnt(3)
	global_store_dwordx4 v5, v[96:99], s[34:35] offset:1024 sc1
	s_waitcnt lgkmcnt(2)
	global_store_dwordx4 v5, v[100:103], s[34:35] offset:1152 sc1
	s_bitcmp1_b32 s9, 1
	s_cbranch_scc1 .Lp0_g_skipst2
	s_waitcnt lgkmcnt(1)
	global_store_dwordx4 v5, v[104:107], s[34:35] offset:1280 sc1
	s_waitcnt lgkmcnt(0)
	global_store_dwordx4 v5, v[108:111], s[34:35] offset:1408 sc1
.Lp0_g_skipst2:
	s_waitcnt lgkmcnt(0)
	s_waitcnt vmcnt(0)
	v_fmac_f32_e32 v148, v136, v48
	v_fmac_f32_e32 v148, v137, v52
	v_fmac_f32_e32 v148, v138, v56
	v_fmac_f32_e32 v148, v139, v60
	v_fmac_f32_e32 v148, v140, v64
	v_fmac_f32_e32 v148, v141, v68
	v_fmac_f32_e32 v148, v142, v72
	v_fmac_f32_e32 v148, v143, v76
	v_fmac_f32_e32 v149, v136, v49
	v_fmac_f32_e32 v149, v137, v53
	v_fmac_f32_e32 v149, v138, v57
	v_fmac_f32_e32 v149, v139, v61
	v_fmac_f32_e32 v149, v140, v65
	v_fmac_f32_e32 v149, v141, v69
	v_fmac_f32_e32 v149, v142, v73
	v_fmac_f32_e32 v149, v143, v77
	v_fmac_f32_e32 v150, v136, v50
	v_fmac_f32_e32 v150, v137, v54
	v_fmac_f32_e32 v150, v138, v58
	v_fmac_f32_e32 v150, v139, v62
	v_fmac_f32_e32 v150, v140, v66
	v_fmac_f32_e32 v150, v141, v70
	v_fmac_f32_e32 v150, v142, v74
	v_fmac_f32_e32 v150, v143, v78
	v_fmac_f32_e32 v151, v136, v51
	v_fmac_f32_e32 v151, v137, v55
	v_fmac_f32_e32 v151, v138, v59
	v_fmac_f32_e32 v151, v139, v63
	v_fmac_f32_e32 v151, v140, v67
	v_fmac_f32_e32 v151, v141, v71
	v_fmac_f32_e32 v151, v142, v75
	v_fmac_f32_e32 v151, v143, v79
	v_mul_f32_e32 v48, v128, v48
	v_mul_f32_e32 v49, v128, v49
	v_mul_f32_e32 v50, v128, v50
	v_mul_f32_e32 v51, v128, v51
	v_mul_f32_e32 v52, v129, v52
	v_mul_f32_e32 v53, v129, v53
	v_mul_f32_e32 v54, v129, v54
	v_mul_f32_e32 v55, v129, v55
	v_mul_f32_e32 v56, v130, v56
	v_mul_f32_e32 v57, v130, v57
	v_mul_f32_e32 v58, v130, v58
	v_mul_f32_e32 v59, v130, v59
	v_mul_f32_e32 v60, v131, v60
	v_mul_f32_e32 v61, v131, v61
	v_mul_f32_e32 v62, v131, v62
	v_mul_f32_e32 v63, v131, v63
	v_mul_f32_e32 v64, v132, v64
	v_mul_f32_e32 v65, v132, v65
	v_mul_f32_e32 v66, v132, v66
	v_mul_f32_e32 v67, v132, v67
	v_mul_f32_e32 v68, v133, v68
	v_mul_f32_e32 v69, v133, v69
	v_mul_f32_e32 v70, v133, v70
	v_mul_f32_e32 v71, v133, v71
	v_mul_f32_e32 v72, v134, v72
	v_mul_f32_e32 v73, v134, v73
	v_mul_f32_e32 v74, v134, v74
	v_mul_f32_e32 v75, v134, v75
	v_mul_f32_e32 v76, v135, v76
	v_mul_f32_e32 v77, v135, v77
	v_mul_f32_e32 v78, v135, v78
	v_mul_f32_e32 v79, v135, v79
	v_cvt_pk_bf16_f32 v80, v48, v52
	v_cvt_pk_bf16_f32 v81, v56, v60
	v_cvt_pk_bf16_f32 v82, v64, v68
	v_cvt_pk_bf16_f32 v83, v72, v76
	v_cvt_pk_bf16_f32 v84, v49, v53
	v_cvt_pk_bf16_f32 v85, v57, v61
	v_cvt_pk_bf16_f32 v86, v65, v69
	v_cvt_pk_bf16_f32 v87, v73, v77
	v_cvt_pk_bf16_f32 v88, v50, v54
	v_cvt_pk_bf16_f32 v89, v58, v62
	v_cvt_pk_bf16_f32 v90, v66, v70
	v_cvt_pk_bf16_f32 v91, v74, v78
	v_cvt_pk_bf16_f32 v92, v51, v55
	v_cvt_pk_bf16_f32 v93, v59, v63
	v_cvt_pk_bf16_f32 v94, v67, v71
	v_cvt_pk_bf16_f32 v95, v75, v79
	v_lshlrev_b32_e32 v152, 16, v80
	v_and_b32_e32 v153, 0xffff0000, v80
	v_add_f32_e32 v144, v144, v152
	v_add_f32_e32 v144, v144, v153
	v_lshlrev_b32_e32 v152, 16, v81
	v_and_b32_e32 v153, 0xffff0000, v81
	v_add_f32_e32 v144, v144, v152
	v_add_f32_e32 v144, v144, v153
	v_lshlrev_b32_e32 v152, 16, v82
	v_and_b32_e32 v153, 0xffff0000, v82
	v_add_f32_e32 v144, v144, v152
	v_add_f32_e32 v144, v144, v153
	v_lshlrev_b32_e32 v152, 16, v83
	v_and_b32_e32 v153, 0xffff0000, v83
	v_add_f32_e32 v144, v144, v152
	v_add_f32_e32 v144, v144, v153
	v_lshlrev_b32_e32 v152, 16, v84
	v_and_b32_e32 v153, 0xffff0000, v84
	v_add_f32_e32 v145, v145, v152
	v_add_f32_e32 v145, v145, v153
	v_lshlrev_b32_e32 v152, 16, v85
	v_and_b32_e32 v153, 0xffff0000, v85
	v_add_f32_e32 v145, v145, v152
	v_add_f32_e32 v145, v145, v153
	v_lshlrev_b32_e32 v152, 16, v86
	v_and_b32_e32 v153, 0xffff0000, v86
	v_add_f32_e32 v145, v145, v152
	v_add_f32_e32 v145, v145, v153
	v_lshlrev_b32_e32 v152, 16, v87
	v_and_b32_e32 v153, 0xffff0000, v87
	v_add_f32_e32 v145, v145, v152
	v_add_f32_e32 v145, v145, v153
	v_lshlrev_b32_e32 v152, 16, v88
	v_and_b32_e32 v153, 0xffff0000, v88
	v_add_f32_e32 v146, v146, v152
	v_add_f32_e32 v146, v146, v153
	v_lshlrev_b32_e32 v152, 16, v89
	v_and_b32_e32 v153, 0xffff0000, v89
	v_add_f32_e32 v146, v146, v152
	v_add_f32_e32 v146, v146, v153
	v_lshlrev_b32_e32 v152, 16, v90
	v_and_b32_e32 v153, 0xffff0000, v90
	v_add_f32_e32 v146, v146, v152
	v_add_f32_e32 v146, v146, v153
	v_lshlrev_b32_e32 v152, 16, v91
	v_and_b32_e32 v153, 0xffff0000, v91
	v_add_f32_e32 v146, v146, v152
	v_add_f32_e32 v146, v146, v153
	v_lshlrev_b32_e32 v152, 16, v92
	v_and_b32_e32 v153, 0xffff0000, v92
	v_add_f32_e32 v147, v147, v152
	v_add_f32_e32 v147, v147, v153
	v_lshlrev_b32_e32 v152, 16, v93
	v_and_b32_e32 v153, 0xffff0000, v93
	v_add_f32_e32 v147, v147, v152
	v_add_f32_e32 v147, v147, v153
	v_lshlrev_b32_e32 v152, 16, v94
	v_and_b32_e32 v153, 0xffff0000, v94
	v_add_f32_e32 v147, v147, v152
	v_add_f32_e32 v147, v147, v153
	v_lshlrev_b32_e32 v152, 16, v95
	v_and_b32_e32 v153, 0xffff0000, v95
	v_add_f32_e32 v147, v147, v152
	v_add_f32_e32 v147, v147, v153
	ds_write_b128 v6, v[80:83] offset:32768
	ds_write_b128 v6, v[84:87] offset:33280
	ds_write_b128 v6, v[88:91] offset:33792
	ds_write_b128 v6, v[92:95] offset:34304
	s_waitcnt lgkmcnt(0)
	s_barrier
	ds_read_b128 v[96:99], v7 offset:32768
	ds_read_b128 v[100:103], v8 offset:32768
	ds_read_b128 v[104:107], v9 offset:32768
	ds_read_b128 v[108:111], v10 offset:32768
	s_cmp_gt_u32 s8, 3
	s_cbranch_scc0 .Lp0_g_skipst3
	s_waitcnt lgkmcnt(3)
	global_store_dwordx4 v5, v[96:99], s[34:35] offset:1536 sc1
	s_waitcnt lgkmcnt(2)
	global_store_dwordx4 v5, v[100:103], s[34:35] offset:1664 sc1
	s_bitcmp1_b32 s9, 1
	s_cbranch_scc1 .Lp0_g_skipst3
	s_waitcnt lgkmcnt(1)
	global_store_dwordx4 v5, v[104:107], s[34:35] offset:1792 sc1
	s_waitcnt lgkmcnt(0)
	global_store_dwordx4 v5, v[108:111], s[34:35] offset:1920 sc1

.Lp0_xloop:
	s_cmp_eq_u32 s50, 0
	s_cbranch_scc1 .Lp0_xtail0
	s_cmpk_lt_u32 s3, 0x1000
	s_cselect_b32 s6, s56, s58
	s_cselect_b32 s7, s57, s59
	s_cselect_b32 s2, 0, 0x1000
	s_sub_u32 s2, s3, s2
	s_lshr_b32 s1, s2, 18
	s_lshl_b32 s2, s2, 14
	s_add_u32 s20, s6, s2
	s_addc_u32 s21, s7, s1
	global_load_dwordx4 v[48:51], v4, s[20:21] nt
	global_load_dwordx4 v[52:55], v4, s[20:21] offset:16 nt
	s_add_u32 s20, s20, 0x4000
	s_addc_u32 s21, s21, 0
	global_load_dwordx4 v[56:59], v4, s[20:21] nt
	global_load_dwordx4 v[60:63], v4, s[20:21] offset:16 nt
	s_add_u32 s3, s3, 2
	s_sub_u32 s50, s50, 1
	s_waitcnt vmcnt(8)
	v_cvt_pk_bf16_f32 v80, v16, v17
	v_cvt_pk_bf16_f32 v81, v18, v19
	v_cvt_pk_bf16_f32 v82, v20, v21
	v_cvt_pk_bf16_f32 v83, v22, v23
	v_cvt_pk_bf16_f32 v84, v24, v25
	v_cvt_pk_bf16_f32 v85, v26, v27
	v_cvt_pk_bf16_f32 v86, v28, v29
	v_cvt_pk_bf16_f32 v87, v30, v31
	global_store_dwordx4 v5, v[80:83], s[48:49] sc1
	global_store_dwordx4 v12, v[84:87], s[48:49] sc1
	s_add_u32 s48, s48, 0x4000
	s_addc_u32 s49, s49, 0
	s_cmp_eq_u32 s50, 0
	s_cbranch_scc1 .Lp0_xtail1
	s_cmpk_lt_u32 s3, 0x1000
	s_cselect_b32 s6, s56, s58
	s_cselect_b32 s7, s57, s59
	s_cselect_b32 s2, 0, 0x1000
	s_sub_u32 s2, s3, s2
	s_lshr_b32 s1, s2, 18
	s_lshl_b32 s2, s2, 14
	s_add_u32 s16, s6, s2
	s_addc_u32 s17, s7, s1
	global_load_dwordx4 v[16:19], v4, s[16:17] nt
	global_load_dwordx4 v[20:23], v4, s[16:17] offset:16 nt
	s_add_u32 s16, s16, 0x4000
	s_addc_u32 s17, s17, 0
	global_load_dwordx4 v[24:27], v4, s[16:17] nt
	global_load_dwordx4 v[28:31], v4, s[16:17] offset:16 nt
	s_add_u32 s3, s3, 2
	s_sub_u32 s50, s50, 1
	s_waitcnt vmcnt(8)
	v_cvt_pk_bf16_f32 v80, v32, v33
	v_cvt_pk_bf16_f32 v81, v34, v35
	v_cvt_pk_bf16_f32 v82, v36, v37
	v_cvt_pk_bf16_f32 v83, v38, v39
	v_cvt_pk_bf16_f32 v84, v40, v41
	v_cvt_pk_bf16_f32 v85, v42, v43
	v_cvt_pk_bf16_f32 v86, v44, v45
	v_cvt_pk_bf16_f32 v87, v46, v47
	global_store_dwordx4 v5, v[80:83], s[48:49] sc1
	global_store_dwordx4 v12, v[84:87], s[48:49] sc1
	s_add_u32 s48, s48, 0x4000
	s_addc_u32 s49, s49, 0
	s_cmp_eq_u32 s50, 0
	s_cbranch_scc1 .Lp0_xtail2
	s_cmpk_lt_u32 s3, 0x1000
	s_cselect_b32 s6, s56, s58
	s_cselect_b32 s7, s57, s59
	s_cselect_b32 s2, 0, 0x1000
	s_sub_u32 s2, s3, s2
	s_lshr_b32 s1, s2, 18
	s_lshl_b32 s2, s2, 14
	s_add_u32 s18, s6, s2
	s_addc_u32 s19, s7, s1
	global_load_dwordx4 v[32:35], v4, s[18:19] nt
	global_load_dwordx4 v[36:39], v4, s[18:19] offset:16 nt
	s_add_u32 s18, s18, 0x4000
	s_addc_u32 s19, s19, 0
	global_load_dwordx4 v[40:43], v4, s[18:19] nt
	global_load_dwordx4 v[44:47], v4, s[18:19] offset:16 nt
	s_add_u32 s3, s3, 2
	s_sub_u32 s50, s50, 1
	s_waitcnt vmcnt(8)
	v_cvt_pk_bf16_f32 v80, v48, v49
	v_cvt_pk_bf16_f32 v81, v50, v51
	v_cvt_pk_bf16_f32 v82, v52, v53
	v_cvt_pk_bf16_f32 v83, v54, v55
	v_cvt_pk_bf16_f32 v84, v56, v57
	v_cvt_pk_bf16_f32 v85, v58, v59
	v_cvt_pk_bf16_f32 v86, v60, v61
	v_cvt_pk_bf16_f32 v87, v62, v63
	global_store_dwordx4 v5, v[80:83], s[48:49] sc1
	global_store_dwordx4 v12, v[84:87], s[48:49] sc1
	s_add_u32 s48, s48, 0x4000
	s_addc_u32 s49, s49, 0
	s_branch .Lp0_xloop
.Lp0_xtail0:
	s_waitcnt vmcnt(4)
	v_cvt_pk_bf16_f32 v80, v16, v17
	v_cvt_pk_bf16_f32 v81, v18, v19
	v_cvt_pk_bf16_f32 v82, v20, v21
	v_cvt_pk_bf16_f32 v83, v22, v23
	v_cvt_pk_bf16_f32 v84, v24, v25
	v_cvt_pk_bf16_f32 v85, v26, v27
	v_cvt_pk_bf16_f32 v86, v28, v29
	v_cvt_pk_bf16_f32 v87, v30, v31
	global_store_dwordx4 v5, v[80:83], s[48:49] sc1
	global_store_dwordx4 v12, v[84:87], s[48:49] sc1
	s_add_u32 s48, s48, 0x4000
	s_addc_u32 s49, s49, 0
	s_waitcnt vmcnt(0)
	v_cvt_pk_bf16_f32 v80, v32, v33
	v_cvt_pk_bf16_f32 v81, v34, v35
	v_cvt_pk_bf16_f32 v82, v36, v37
	v_cvt_pk_bf16_f32 v83, v38, v39
	v_cvt_pk_bf16_f32 v84, v40, v41
	v_cvt_pk_bf16_f32 v85, v42, v43
	v_cvt_pk_bf16_f32 v86, v44, v45
	v_cvt_pk_bf16_f32 v87, v46, v47
	global_store_dwordx4 v5, v[80:83], s[48:49] sc1
	global_store_dwordx4 v12, v[84:87], s[48:49] sc1
	s_add_u32 s48, s48, 0x4000
	s_addc_u32 s49, s49, 0
	s_branch .Lp0_stzero
.Lp0_xtail1:
	s_waitcnt vmcnt(4)
	v_cvt_pk_bf16_f32 v80, v32, v33
	v_cvt_pk_bf16_f32 v81, v34, v35
	v_cvt_pk_bf16_f32 v82, v36, v37
	v_cvt_pk_bf16_f32 v83, v38, v39
	v_cvt_pk_bf16_f32 v84, v40, v41
	v_cvt_pk_bf16_f32 v85, v42, v43
	v_cvt_pk_bf16_f32 v86, v44, v45
	v_cvt_pk_bf16_f32 v87, v46, v47
	global_store_dwordx4 v5, v[80:83], s[48:49] sc1
	global_store_dwordx4 v12, v[84:87], s[48:49] sc1
	s_add_u32 s48, s48, 0x4000
	s_addc_u32 s49, s49, 0
	s_waitcnt vmcnt(0)
	v_cvt_pk_bf16_f32 v80, v48, v49
	v_cvt_pk_bf16_f32 v81, v50, v51
	v_cvt_pk_bf16_f32 v82, v52, v53
	v_cvt_pk_bf16_f32 v83, v54, v55
	v_cvt_pk_bf16_f32 v84, v56, v57
	v_cvt_pk_bf16_f32 v85, v58, v59
	v_cvt_pk_bf16_f32 v86, v60, v61
	v_cvt_pk_bf16_f32 v87, v62, v63
	global_store_dwordx4 v5, v[80:83], s[48:49] sc1
	global_store_dwordx4 v12, v[84:87], s[48:49] sc1
	s_add_u32 s48, s48, 0x4000
	s_addc_u32 s49, s49, 0
	s_branch .Lp0_stzero
.Lp0_xtail2:
	s_waitcnt vmcnt(4)
	v_cvt_pk_bf16_f32 v80, v48, v49
	v_cvt_pk_bf16_f32 v81, v50, v51
	v_cvt_pk_bf16_f32 v82, v52, v53
	v_cvt_pk_bf16_f32 v83, v54, v55
	v_cvt_pk_bf16_f32 v84, v56, v57
	v_cvt_pk_bf16_f32 v85, v58, v59
	v_cvt_pk_bf16_f32 v86, v60, v61
	v_cvt_pk_bf16_f32 v87, v62, v63
	global_store_dwordx4 v5, v[80:83], s[48:49] sc1
	global_store_dwordx4 v12, v[84:87], s[48:49] sc1
	s_add_u32 s48, s48, 0x4000
	s_addc_u32 s49, s49, 0
	s_waitcnt vmcnt(0)
	v_cvt_pk_bf16_f32 v80, v16, v17
	v_cvt_pk_bf16_f32 v81, v18, v19
	v_cvt_pk_bf16_f32 v82, v20, v21
	v_cvt_pk_bf16_f32 v83, v22, v23
	v_cvt_pk_bf16_f32 v84, v24, v25
	v_cvt_pk_bf16_f32 v85, v26, v27
	v_cvt_pk_bf16_f32 v86, v28, v29
	v_cvt_pk_bf16_f32 v87, v30, v31
	global_store_dwordx4 v5, v[80:83], s[48:49] sc1
	global_store_dwordx4 v12, v[84:87], s[48:49] sc1
	s_add_u32 s48, s48, 0x4000
	s_addc_u32 s49, s49, 0
	s_branch .Lp0_stzero
